# NSA sel/window loops: V fragments read with ds_read_b64 pairs instead of ds_read2_b64 (plus v22 changes)
# speedup vs baseline: 1.0109x; 1.0044x over previous
; #define LAS __attribute__((address_space(3)))
; #define MFMA32(a, b, c) __builtin_amdgcn_mfma_f32_32x32x16_bf16((a), (b), (c), 0, 0, 0)
; DI int ccol(int r) { return (r & 3) + 8 * (r >> 2); }
; DI void tile_scores(f32x16& x0, f32x16& x1, const LAS unsigned char* buf, const bf16x8 (&qf)[4], float sk, float aref, int p0, bool laneok, bool needmask, int lo, int hip, int r32, int hi) {
;     KFrag K0, K1; lds_k(K0, buf, 0, r32, hi); lds_k(K1, buf, 1, r32, hi);
;     const float B = laneok ? fmaf(sk, (float)(p0 + 4 * hi), -aref) : -1e30f;
;     const float B1 = B + 32.f * sk;
; #pragma unroll
;     for (int r = 0; r < 16; ++r) { x0[r] = fmaf(sk, (float)ccol(r), B); x1[r] = fmaf(sk, (float)ccol(r), B1); }
; #pragma unroll
;     for (int d0 = 0; d0 < 4; ++d0) { x0 = MFMA32(K0.k[d0], qf[d0], x0); x1 = MFMA32(K1.k[d0], qf[d0], x1); }
; DI void nsa_unit(const bf16* PR, const bf16* VT, const bf16* kcb, const bf16* vctb, bf16* Y, LAS unsigned char* lds, int b, int g, int jt) {
;     ...
;             const unsigned wuw = jw == 0 ? wu0 : (jw == 1 ? wu1 : (jw == 2 ? wu2 : wu3));
;             if ((wuw >> jb) & 1u) {
;                 const unsigned mw = jw == 0 ? mk0 : (jw == 1 ? mk1 : (jw == 2 ? mk2 : mk3));
;                 const bool mysel = (mw >> jb) & 1u;
;                 VFrag V0, V1; lds_v(V0, buf, 0, r32, hi); lds_v(V1, buf, 1, r32, hi);
;                 f32x16 x0, x1; tile_scores(x0, x1, buf, qf, slope2, ab + f.mref, 64 * jcur, mysel, jcur == jt, -(1 << 30), t, r32, hi);
.LBB0_996:
	s_lshr_b32 s8, s10, 5
	s_cmp_eq_u32 s8, 2
	s_cselect_b64 vcc, -1, 0
	s_and_b64 s[6:7], vcc, exec
	s_cselect_b32 s11, s50, s52
	s_cmp_eq_u32 s8, 1
	s_cselect_b64 s[6:7], -1, 0
	s_and_b64 s[8:9], s[6:7], exec
	s_cselect_b32 s11, s48, s11
	s_cmp_lt_u32 s10, 32
	s_cselect_b64 s[8:9], -1, 0
	s_and_b64 s[12:13], s[8:9], exec
	s_cselect_b32 s12, s46, s11
	s_lshl_b32 s11, 1, s10
	s_and_b32 s12, s12, s11
	s_cmp_eq_u32 s12, 0
	s_cbranch_scc1 .LBB0_1008
	v_cndmask_b32_e32 v1, v115, v114, vcc
	v_cndmask_b32_e64 v1, v1, v113, s[6:7]
	v_cndmask_b32_e64 v1, v1, v112, s[8:9]
	v_and_b32_e32 v14, s11, v1
	v_lshl_or_b32 v1, s10, 6, v240
	v_cvt_f32_u32_e32 v80, v1
	s_mul_i32 s12, s2, 0x4600
	s_add_i32 s12, s12, 0
	v_add_f32_e32 v15, v247, v167
	v_add3_u32 v128, s12, v245, v206
	v_fma_f32 v15, v208, v80, -v15
	v_cmp_ne_u32_e32 vcc, 0, v14
	ds_read_b128 v[2:5], v128
	ds_read_b128 v[6:9], v128 offset:32
	ds_read_b128 v[10:13], v128 offset:4608
	ds_read_b128 v[124:127], v128 offset:4640
	v_cndmask_b32_e32 v14, v222, v15, vcc
	v_fma_f32 v96, 0, v208, v14
	v_add_f32_e32 v97, v208, v14
	v_pk_fma_f32 v[98:99], v[208:209], s[82:83], v[14:15] op_sel_hi:[1,1,0]
	v_pk_fma_f32 v[100:101], v[208:209], s[84:85], v[14:15] op_sel_hi:[1,1,0]
	v_pk_fma_f32 v[102:103], v[208:209], s[86:87], v[14:15] op_sel_hi:[1,1,0]
	v_pk_fma_f32 v[104:105], v[208:209], s[80:81], v[14:15] op_sel_hi:[1,1,0]
	v_pk_fma_f32 v[106:107], v[208:209], s[88:89], v[14:15] op_sel_hi:[1,1,0]
	v_pk_fma_f32 v[108:109], v[208:209], s[90:91], v[14:15] op_sel_hi:[1,1,0]
	v_pk_fma_f32 v[110:111], v[208:209], s[92:93], v[14:15] op_sel_hi:[1,1,0]
	v_add_f32_e32 v94, v166, v14
	v_fma_f32 v80, 0, v208, v94
	s_waitcnt lgkmcnt(3)
	v_mfma_f32_32x32x16_bf16 v[96:111], v[2:5], v[144:147], v[96:111]
	v_add_f32_e32 v81, v208, v94
	v_fma_f32 v82, v208, s82, v94
	v_fma_f32 v83, v209, s83, v94
	v_fma_f32 v84, v208, s84, v94
	v_fma_f32 v85, v209, s85, v94
	v_pk_fma_f32 v[86:87], v[208:209], s[86:87], v[94:95] op_sel_hi:[1,1,0]
	v_pk_fma_f32 v[88:89], v[208:209], s[80:81], v[94:95] op_sel_hi:[1,1,0]
	v_pk_fma_f32 v[90:91], v[208:209], s[88:89], v[94:95] op_sel_hi:[1,1,0]
	v_pk_fma_f32 v[92:93], v[208:209], s[90:91], v[94:95] op_sel_hi:[1,1,0]
	v_pk_fma_f32 v[94:95], v[208:209], s[92:93], v[94:95] op_sel_hi:[1,1,0]
	s_waitcnt lgkmcnt(2)
	v_mfma_f32_32x32x16_bf16 v[96:111], v[6:9], v[148:151], v[96:111]
	ds_read_b128 v[2:5], v128 offset:64
	ds_read_b128 v[6:9], v128 offset:96
	s_cmp_lg_u32 s10, s72
	s_waitcnt lgkmcnt(3)
	v_mfma_f32_32x32x16_bf16 v[80:95], v[10:13], v[144:147], v[80:95]
	s_waitcnt lgkmcnt(2)
	v_mfma_f32_32x32x16_bf16 v[80:95], v[124:127], v[148:151], v[80:95]
	s_waitcnt lgkmcnt(1)
	v_mfma_f32_32x32x16_bf16 v[96:111], v[2:5], v[152:155], v[96:111]
	ds_read_b128 v[2:5], v128 offset:4672
	ds_read_b128 v[174:177], v128 offset:4704
	s_waitcnt lgkmcnt(1)
	v_mfma_f32_32x32x16_bf16 v[80:95], v[2:5], v[152:155], v[80:95]
	v_add3_u32 v2, s12, v207, v244
	v_add_u32_e32 v3, 0x2000, v2
	v_add_u32_e32 v2, 0x3000, v2
	ds_read_b64 v[140:141], v3 offset:1024
	ds_read_b64 v[142:143], v3 offset:1040
	ds_read_b64 v[132:133], v3 offset:1056
	ds_read_b64 v[134:135], v3 offset:1072
	v_mfma_f32_32x32x16_bf16 v[96:111], v[6:9], v[156:159], v[96:111]
	ds_read_b64 v[136:137], v2 offset:1280
	ds_read_b64 v[138:139], v2 offset:1296
	ds_read_b64 v[128:129], v2 offset:1312
	ds_read_b64 v[130:131], v2 offset:1328
	ds_read_b64 v[124:125], v3 offset:1088
	ds_read_b64 v[126:127], v3 offset:1104
	ds_read_b64 v[10:11], v2 offset:1344
	ds_read_b64 v[12:13], v2 offset:1360
	ds_read_b64 v[6:7], v3 offset:1120
	ds_read_b64 v[8:9], v3 offset:1136
	ds_read_b64 v[4:5], v2 offset:1392
	ds_read_b64 v[2:3], v2 offset:1376
	s_waitcnt lgkmcnt(15)
	v_mfma_f32_32x32x16_bf16 v[80:95], v[174:177], v[156:159], v[80:95]
	s_cbranch_scc1 .LBB0_1001
; DI int crow(int r, int hi) { return (r & 3) + 8 * (r >> 2) + 4 * hi; }
; DI void tile_scores(f32x16& x0, f32x16& x1, const LAS unsigned char* buf, const bf16x8 (&qf)[4], float sk, float aref, int p0, bool laneok, bool needmask, int lo, int hip, int r32, int hi) {
;     ...
;     if (needmask) {
; #pragma unroll
;         for (int r = 0; r < 16; ++r) { const int pos = p0 + crow(r, hi); if (pos < lo || pos > hip) x0[r] = -1e30f; if (pos + 32 < lo || pos + 32 > hip) x1[r] = -1e30f; }
;     }
	v_or_b32_e32 v14, 32, v1
	v_cmp_le_i32_e64 s[6:7], v14, v204
	v_or_b32_e32 v14, 33, v1
	v_cmp_le_i32_e64 s[8:9], v14, v204
	v_or_b32_e32 v14, 2, v1
	v_cmp_le_i32_e32 vcc, v1, v204
	s_nop 4
	v_cndmask_b32_e64 v81, v222, v81, s[8:9]
	v_cmp_le_i32_e64 s[8:9], v14, v204
	v_or_b32_e32 v14, 34, v1
	v_cmp_le_i32_e64 s[10:11], v14, v204
	v_or_b32_e32 v14, 3, v1
	v_cndmask_b32_e64 v80, v222, v80, s[6:7]
	v_cndmask_b32_e64 v82, v222, v82, s[10:11]
	v_cmp_le_i32_e64 s[10:11], v14, v204
	v_or_b32_e32 v14, 35, v1
	v_cmp_le_i32_e64 s[12:13], v14, v204
	v_or_b32_e32 v14, 8, v1
	v_cmp_lt_i32_e64 s[6:7], v1, v204
	v_cndmask_b32_e64 v83, v222, v83, s[12:13]
	v_cmp_le_i32_e64 s[12:13], v14, v204
	v_or_b32_e32 v14, 40, v1
	v_cmp_le_i32_e64 s[14:15], v14, v204
	v_or_b32_e32 v14, 9, v1
	s_nop 0
	v_cndmask_b32_e64 v84, v222, v84, s[14:15]
	v_cmp_le_i32_e64 s[14:15], v14, v204
	v_or_b32_e32 v14, 41, v1
	v_cmp_le_i32_e64 s[16:17], v14, v204
	v_or_b32_e32 v14, 10, v1
	s_nop 0
	v_cndmask_b32_e64 v85, v222, v85, s[16:17]
	v_cmp_le_i32_e64 s[16:17], v14, v204
	v_or_b32_e32 v14, 42, v1
	v_cmp_le_i32_e64 s[18:19], v14, v204
	v_or_b32_e32 v14, 11, v1
	s_nop 0
	v_cndmask_b32_e64 v86, v222, v86, s[18:19]
	v_cmp_le_i32_e64 s[18:19], v14, v204
	v_or_b32_e32 v14, 43, v1
	v_cmp_le_i32_e64 s[20:21], v14, v204
	v_or_b32_e32 v14, 16, v1
	s_nop 0
	v_cndmask_b32_e64 v87, v222, v87, s[20:21]
	v_cmp_le_i32_e64 s[20:21], v14, v204
	v_or_b32_e32 v14, 48, v1
	v_cmp_le_i32_e64 s[22:23], v14, v204
	v_or_b32_e32 v14, 17, v1
	s_nop 0
	v_cndmask_b32_e64 v88, v222, v88, s[22:23]
	v_cmp_le_i32_e64 s[22:23], v14, v204
	v_or_b32_e32 v14, 49, v1
	v_cmp_le_i32_e64 s[24:25], v14, v204
	v_or_b32_e32 v14, 18, v1
	s_nop 0
	v_cndmask_b32_e64 v89, v222, v89, s[24:25]
	v_cmp_le_i32_e64 s[24:25], v14, v204
	v_or_b32_e32 v14, 50, v1
	v_cmp_le_i32_e64 s[26:27], v14, v204
	v_or_b32_e32 v14, 19, v1
	s_nop 0
	v_cndmask_b32_e64 v90, v222, v90, s[26:27]
	v_cmp_le_i32_e64 s[26:27], v14, v204
	v_or_b32_e32 v14, 51, v1
	v_cmp_le_i32_e64 s[28:29], v14, v204
	v_or_b32_e32 v14, 24, v1
	s_nop 0
	v_cndmask_b32_e64 v91, v222, v91, s[28:29]
	v_cmp_le_i32_e64 s[28:29], v14, v204
	v_or_b32_e32 v14, 56, v1
	v_cmp_le_i32_e64 s[30:31], v14, v204
	v_or_b32_e32 v14, 25, v1
	s_nop 0
	v_cndmask_b32_e64 v92, v222, v92, s[30:31]
	v_cmp_le_i32_e64 s[30:31], v14, v204
	v_or_b32_e32 v14, 57, v1
	v_cmp_le_i32_e64 s[34:35], v14, v204
	v_or_b32_e32 v14, 26, v1
	s_nop 0
	v_cndmask_b32_e64 v93, v222, v93, s[34:35]
	v_cmp_le_i32_e64 s[34:35], v14, v204
	v_or_b32_e32 v14, 58, v1
	v_cmp_le_i32_e64 s[36:37], v14, v204
	v_or_b32_e32 v14, 27, v1
	v_or_b32_e32 v1, 59, v1
	v_cndmask_b32_e64 v94, v222, v94, s[36:37]
	v_cmp_le_i32_e64 s[36:37], v14, v204
	v_cmp_gt_i32_e64 s[38:39], v1, v204
	s_and_saveexec_b64 s[44:45], s[38:39]
	v_mov_b32_e32 v95, s75
	s_or_b64 exec, exec, s[44:45]
	v_cndmask_b32_e64 v97, v222, v97, s[6:7]
	v_cndmask_b32_e32 v96, v222, v96, vcc
	v_cndmask_b32_e64 v98, v222, v98, s[8:9]
	v_cndmask_b32_e64 v99, v222, v99, s[10:11]
	v_cndmask_b32_e64 v100, v222, v100, s[12:13]
	v_cndmask_b32_e64 v101, v222, v101, s[14:15]
	v_cndmask_b32_e64 v102, v222, v102, s[16:17]
	v_cndmask_b32_e64 v103, v222, v103, s[18:19]
	v_cndmask_b32_e64 v104, v222, v104, s[20:21]
	v_cndmask_b32_e64 v105, v222, v105, s[22:23]
	v_cndmask_b32_e64 v106, v222, v106, s[24:25]
	v_cndmask_b32_e64 v107, v222, v107, s[26:27]
	v_cndmask_b32_e64 v108, v222, v108, s[28:29]
	v_cndmask_b32_e64 v109, v222, v109, s[30:31]
	v_cndmask_b32_e64 v110, v222, v110, s[34:35]
	v_cndmask_b32_e64 v111, v222, v111, s[36:37]

; DI unsigned pk2(float lo, float hi) { f32x2 v = {lo, hi}; return __builtin_bit_cast(unsigned, __builtin_convertvector(v, bf2_t)); }
; DI float fast_exp2(float x) { return __builtin_amdgcn_exp2f(x); }
; #define MFMA32(a, b, c) __builtin_amdgcn_mfma_f32_32x32x16_bf16((a), (b), (c), 0, 0, 0)
; DI void pv_frag(const VFrag& V, const f32x16& p, f32x16& o0, f32x16& o1) {
; #pragma unroll
;     for (int s = 0; s < 2; ++s) {
;         u32x4 pw; pw.x = pk2(p[8 * s], p[8 * s + 1]); pw.y = pk2(p[8 * s + 2], p[8 * s + 3]); pw.z = pk2(p[8 * s + 4], p[8 * s + 5]); pw.w = pk2(p[8 * s + 6], p[8 * s + 7]);
;         const bf16x8 pf = __builtin_bit_cast(bf16x8, pw);
; #pragma unroll
;         for (int d0 = 0; d0 < 2; ++d0) {
;             const u32x2 lo = V.v[(2 * s + d0) * 2], h2 = V.v[(2 * s + d0) * 2 + 1];
;             u32x4 vw; vw.x = lo.x; vw.y = lo.y; vw.z = h2.x; vw.w = h2.y;
;             const bf16x8 vf = __builtin_bit_cast(bf16x8, vw);
;             if (d0 == 0) o0 = MFMA32(vf, pf, o0); else o1 = MFMA32(vf, pf, o1);
;         }
;     }
; }
; DI float soft_update(Soft& f, f32x16& x0, f32x16& x1, bool hasO) {
;     ...
;     float ls = 0.f;
; #pragma unroll
;     for (int r = 0; r < 16; ++r) { x0[r] = fast_exp2(x0[r]); x1[r] = fast_exp2(x1[r]); ls += x0[r] + x1[r]; }
;     f.l += ls;
.LBB0_1007:
	v_exp_f32_e32 v1, v96
	v_exp_f32_e32 v171, v80
	v_exp_f32_e32 v14, v97
	v_exp_f32_e32 v96, v81
	v_mov_b32_e32 v15, v0
	v_add_f32_e32 v97, v171, v1
	s_or_b64 s[4:5], s[4:5], s[6:7]
	v_pk_add_f32 v[80:81], v[96:97], v[14:15]
	v_exp_f32_e32 v15, v98
	v_pk_add_f32 v[174:175], v[80:81], v[80:81] op_sel_hi:[0,1]
	v_exp_f32_e32 v97, v82
	v_exp_f32_e32 v174, v99
	v_exp_f32_e32 v98, v83
	v_add_f32_e32 v99, v97, v15
	v_pk_add_f32 v[80:81], v[98:99], v[174:175]
	s_nop 0
	v_pk_add_f32 v[82:83], v[80:81], v[80:81] op_sel_hi:[0,1]
	v_exp_f32_e32 v99, v100
	v_exp_f32_e32 v175, v84
	v_exp_f32_e32 v82, v101
	v_exp_f32_e32 v84, v85
	v_add_f32_e32 v85, v175, v99
	v_pk_add_f32 v[80:81], v[84:85], v[82:83]
	s_nop 0
	v_pk_add_f32 v[100:101], v[80:81], v[80:81] op_sel_hi:[0,1]
	v_exp_f32_e32 v83, v102
	v_exp_f32_e32 v85, v86
	v_exp_f32_e32 v100, v103
	v_exp_f32_e32 v86, v87
	v_cvt_pk_bf16_f32 v82, v99, v82
	v_add_f32_e32 v87, v85, v83
	v_cvt_pk_bf16_f32 v83, v83, v100
	v_pk_add_f32 v[80:81], v[86:87], v[100:101]
	v_exp_f32_e32 v87, v104
	v_pk_add_f32 v[102:103], v[80:81], v[80:81] op_sel_hi:[0,1]
	v_exp_f32_e32 v101, v88
	v_exp_f32_e32 v102, v105
	v_exp_f32_e32 v88, v89
	v_add_f32_e32 v89, v101, v87
	v_pk_add_f32 v[80:81], v[88:89], v[102:103]
	s_nop 0
	v_pk_add_f32 v[104:105], v[80:81], v[80:81] op_sel_hi:[0,1]
	v_exp_f32_e32 v89, v106
	v_exp_f32_e32 v103, v90
	v_exp_f32_e32 v104, v107
	v_exp_f32_e32 v90, v91
	v_add_f32_e32 v91, v103, v89
	v_pk_add_f32 v[80:81], v[90:91], v[104:105]
	s_nop 0
	v_pk_add_f32 v[106:107], v[80:81], v[80:81] op_sel_hi:[0,1]
	v_exp_f32_e32 v91, v108
	v_cvt_pk_bf16_f32 v80, v1, v14
	v_exp_f32_e32 v1, v92
	v_exp_f32_e32 v106, v109
	v_exp_f32_e32 v14, v93
	v_cvt_pk_bf16_f32 v81, v15, v174
	v_add_f32_e32 v15, v1, v91
	v_pk_add_f32 v[92:93], v[14:15], v[106:107]
	s_waitcnt lgkmcnt(14)
	v_mfma_f32_32x32x16_bf16 v[64:79], v[140:143], v[80:83], v[64:79]
	v_pk_add_f32 v[92:93], v[92:93], v[92:93] op_sel_hi:[0,1]
	v_exp_f32_e32 v15, v110
	v_exp_f32_e32 v92, v111
	s_waitcnt lgkmcnt(10)
	v_mfma_f32_32x32x16_bf16 v[48:63], v[136:139], v[80:83], v[48:63]
	v_cvt_pk_bf16_f32 v80, v87, v102
	v_cvt_pk_bf16_f32 v81, v89, v104
	v_cvt_pk_bf16_f32 v82, v91, v106
	v_cvt_pk_bf16_f32 v83, v15, v92
	s_nop 1
	v_mfma_f32_32x32x16_bf16 v[64:79], v[132:135], v[80:83], v[64:79]
	s_waitcnt lgkmcnt(8)
	v_mfma_f32_32x32x16_bf16 v[48:63], v[128:131], v[80:83], v[48:63]
	v_cvt_pk_bf16_f32 v80, v171, v96
	v_cvt_pk_bf16_f32 v81, v97, v98
	v_cvt_pk_bf16_f32 v82, v175, v84
	v_cvt_pk_bf16_f32 v83, v85, v86
	s_waitcnt lgkmcnt(6)
	s_nop 0
	v_mfma_f32_32x32x16_bf16 v[64:79], v[124:127], v[80:83], v[64:79]
	s_waitcnt lgkmcnt(4)
	v_mfma_f32_32x32x16_bf16 v[48:63], v[10:13], v[80:83], v[48:63]
	v_exp_f32_e32 v81, v94
	v_exp_f32_e32 v80, v95
	v_cvt_pk_bf16_f32 v10, v101, v88
	v_cvt_pk_bf16_f32 v11, v103, v90
	v_cvt_pk_bf16_f32 v12, v1, v14
	v_cvt_pk_bf16_f32 v13, v81, v80
	v_add_f32_e32 v81, v81, v15
	s_waitcnt lgkmcnt(2)
	v_mfma_f32_32x32x16_bf16 v[64:79], v[6:9], v[10:13], v[64:79]
	v_add_f32_e64 v6, v80, v92
	v_add_f32_e64 v7, v81, v93
	v_add_f32_e32 v1, v6, v7
	v_add_f32_e32 v211, v211, v1
	s_waitcnt lgkmcnt(0)
	v_mfma_f32_32x32x16_bf16 v[48:63], v[2:5], v[10:13], v[48:63]

; #define LAS __attribute__((address_space(3)))
; #define MFMA32(a, b, c) __builtin_amdgcn_mfma_f32_32x32x16_bf16((a), (b), (c), 0, 0, 0)
; DI int ccol(int r) { return (r & 3) + 8 * (r >> 2); }
; DI void tile_scores(f32x16& x0, f32x16& x1, const LAS unsigned char* buf, const bf16x8 (&qf)[4], float sk, float aref, int p0, bool laneok, bool needmask, int lo, int hip, int r32, int hi) {
;     KFrag K0, K1; lds_k(K0, buf, 0, r32, hi); lds_k(K1, buf, 1, r32, hi);
;     const float B = laneok ? fmaf(sk, (float)(p0 + 4 * hi), -aref) : -1e30f;
;     const float B1 = B + 32.f * sk;
; #pragma unroll
;     for (int r = 0; r < 16; ++r) { x0[r] = fmaf(sk, (float)ccol(r), B); x1[r] = fmaf(sk, (float)ccol(r), B1); }
; #pragma unroll
;     for (int d0 = 0; d0 < 4; ++d0) { x0 = MFMA32(K0.k[d0], qf[d0], x0); x1 = MFMA32(K1.k[d0], qf[d0], x1); }
; DI void nsa_unit(const bf16* PR, const bf16* VT, const bf16* kcb, const bf16* vctb, bf16* Y, LAS unsigned char* lds, int b, int g, int jt) {
;     ...
;         for (int kt = klast; kt >= kfirst; kt -= 64) {
;             if (kt - 64 >= kfirst) stage_load(R, kw + (size_t)(kt - 64) * 64, 64, vwt + kt - 64, SEQ, tid, true);
;             const LAS unsigned char* buf = tb + par * TBUF;
;             if (kt + 63 >= tw0 - 511) {
;                 const bool needmask = (kt + 63 > tw0) || (kt < tw0 + 31 - 511);
;                 VFrag V0, V1; lds_v(V0, buf, 0, r32, hi); lds_v(V1, buf, 1, r32, hi);
;                 f32x16 x0, x1; tile_scores(x0, x1, buf, qf, slope2, ab + f.mref, kt, true, needmask, t - 511, t, r32, hi);
.LBB0_1020:
	v_add_u32_e32 v14, s94, v240
	v_add_u32_e32 v15, 64, v14
	v_cvt_f32_u32_e32 v113, v15
	s_mul_i32 s7, s1, 0x4600
	s_add_i32 s10, s7, 0
	v_add_f32_e32 v112, v247, v1
	v_add3_u32 v172, s10, v245, v206
	ds_read_b128 v[2:5], v172
	ds_read_b128 v[6:9], v172 offset:32
	ds_read_b128 v[10:13], v172 offset:4608
	ds_read_b128 v[168:171], v172 offset:4640
	v_fma_f32 v114, v208, v113, -v112
	v_fma_f32 v128, 0, v208, v114
	v_add_f32_e32 v129, v208, v114
	v_pk_fma_f32 v[130:131], v[208:209], s[82:83], v[114:115] op_sel_hi:[1,1,0]
	v_pk_fma_f32 v[132:133], v[208:209], s[84:85], v[114:115] op_sel_hi:[1,1,0]
	v_pk_fma_f32 v[134:135], v[208:209], s[86:87], v[114:115] op_sel_hi:[1,1,0]
	v_pk_fma_f32 v[136:137], v[208:209], s[80:81], v[114:115] op_sel_hi:[1,1,0]
	v_pk_fma_f32 v[138:139], v[208:209], s[88:89], v[114:115] op_sel_hi:[1,1,0]
	v_pk_fma_f32 v[140:141], v[208:209], s[90:91], v[114:115] op_sel_hi:[1,1,0]
	v_pk_fma_f32 v[142:143], v[208:209], s[92:93], v[114:115] op_sel_hi:[1,1,0]
	v_add_f32_e32 v126, v248, v114
	v_fma_f32 v112, 0, v208, v126
	s_waitcnt lgkmcnt(3)
	v_mfma_f32_32x32x16_bf16 v[128:143], v[2:5], v[144:147], v[128:143]
	v_add_f32_e32 v113, v208, v126
	v_fma_f32 v114, v208, s82, v126
	v_fma_f32 v115, v209, s83, v126
	v_fma_f32 v116, v208, s84, v126
	v_fma_f32 v117, v209, s85, v126
	v_pk_fma_f32 v[118:119], v[208:209], s[86:87], v[126:127] op_sel_hi:[1,1,0]
	v_pk_fma_f32 v[120:121], v[208:209], s[80:81], v[126:127] op_sel_hi:[1,1,0]
	v_pk_fma_f32 v[122:123], v[208:209], s[88:89], v[126:127] op_sel_hi:[1,1,0]
	v_pk_fma_f32 v[124:125], v[208:209], s[90:91], v[126:127] op_sel_hi:[1,1,0]
	v_pk_fma_f32 v[126:127], v[208:209], s[92:93], v[126:127] op_sel_hi:[1,1,0]
	s_waitcnt lgkmcnt(2)
	v_mfma_f32_32x32x16_bf16 v[128:143], v[6:9], v[148:151], v[128:143]
	ds_read_b128 v[2:5], v172 offset:64
	ds_read_b128 v[6:9], v172 offset:96
	ds_read_b128 v[250:253], v172 offset:4704
	s_cmp_gt_i32 s6, s71
	s_cselect_b64 s[6:7], -1, 0
	s_cmp_lt_i32 s78, s0
	s_cselect_b64 s[8:9], -1, 0
	s_or_b64 s[6:7], s[6:7], s[8:9]
	s_waitcnt lgkmcnt(4)
	v_mfma_f32_32x32x16_bf16 v[112:127], v[10:13], v[144:147], v[112:127]
	v_add3_u32 v10, s10, v207, v244
	s_andn2_b64 vcc, exec, s[6:7]
	s_waitcnt lgkmcnt(2)
	v_mfma_f32_32x32x16_bf16 v[128:143], v[2:5], v[152:155], v[128:143]
	ds_read_b128 v[2:5], v172 offset:4672
	v_mfma_f32_32x32x16_bf16 v[112:127], v[168:171], v[148:151], v[112:127]
	s_waitcnt lgkmcnt(0)
	v_mfma_f32_32x32x16_bf16 v[112:127], v[2:5], v[152:155], v[112:127]
	v_add_u32_e32 v2, 0x2000, v10
	v_add_u32_e32 v3, 0x3000, v10
	ds_read_b64 v[184:185], v2 offset:1024
	ds_read_b64 v[186:187], v2 offset:1040
	ds_read_b64 v[176:177], v2 offset:1056
	ds_read_b64 v[178:179], v2 offset:1072
	ds_read_b64 v[180:181], v3 offset:1280
	ds_read_b64 v[182:183], v3 offset:1296
	ds_read_b64 v[172:173], v3 offset:1312
	ds_read_b64 v[174:175], v3 offset:1328
	ds_read_b64 v[168:169], v2 offset:1088
	ds_read_b64 v[170:171], v2 offset:1104
	v_mfma_f32_32x32x16_bf16 v[128:143], v[6:9], v[156:159], v[128:143]
	ds_read_b64 v[10:11], v3 offset:1344
	ds_read_b64 v[12:13], v3 offset:1360
	ds_read_b64 v[6:7], v2 offset:1120
	ds_read_b64 v[8:9], v2 offset:1136
	ds_read_b64 v[4:5], v3 offset:1392
	ds_read_b64 v[2:3], v3 offset:1376
	v_mfma_f32_32x32x16_bf16 v[112:127], v[250:253], v[156:159], v[112:127]
	s_cbranch_vccnz .LBB0_1024
; DI int crow(int r, int hi) { return (r & 3) + 8 * (r >> 2) + 4 * hi; }
; DI void tile_scores(f32x16& x0, f32x16& x1, const LAS unsigned char* buf, const bf16x8 (&qf)[4], float sk, float aref, int p0, bool laneok, bool needmask, int lo, int hip, int r32, int hi) {
;     ...
;     if (needmask) {
; #pragma unroll
;         for (int r = 0; r < 16; ++r) { const int pos = p0 + crow(r, hi); if (pos < lo || pos > hip) x0[r] = -1e30f; if (pos + 32 < lo || pos + 32 > hip) x1[r] = -1e30f; }
;     }
; DI void nsa_unit(const bf16* PR, const bf16* VT, const bf16* kcb, const bf16* vctb, bf16* Y, LAS unsigned char* lds, int b, int g, int jt) {
;     ...
;                 const bool needmask = (kt + 63 > tw0) || (kt < tw0 + 31 - 511);
;                 VFrag V0, V1; lds_v(V0, buf, 0, r32, hi); lds_v(V1, buf, 1, r32, hi);
;                 f32x16 x0, x1; tile_scores(x0, x1, buf, qf, slope2, ab + f.mref, kt, true, needmask, t - 511, t, r32, hi);
	v_add_u32_e32 v250, 0x60, v14
	v_cmp_lt_i32_e64 s[8:9], v250, v249
	v_cmp_gt_i32_e64 s[10:11], v250, v204
	v_cmp_lt_i32_e32 vcc, v15, v249
	v_cmp_gt_i32_e64 s[6:7], v15, v204
	s_or_b64 s[8:9], s[8:9], s[10:11]
	v_cmp_ge_i32_e64 s[10:11], v15, v204
	v_add_u32_e32 v15, 0x61, v14
	v_cmp_lt_i32_e64 s[12:13], v15, v249
	v_cmp_gt_i32_e64 s[14:15], v15, v204
	s_or_b64 s[12:13], s[12:13], s[14:15]
	v_add_u32_e32 v15, 0x42, v14
	v_cndmask_b32_e64 v113, v113, v222, s[12:13]
	v_cmp_lt_i32_e64 s[12:13], v15, v249
	v_cmp_gt_i32_e64 s[14:15], v15, v204
	v_add_u32_e32 v15, 0x62, v14
	v_cmp_lt_i32_e64 s[16:17], v15, v249
	v_cmp_gt_i32_e64 s[18:19], v15, v204
	s_or_b64 s[16:17], s[16:17], s[18:19]
	v_add_u32_e32 v15, 0x43, v14
	v_cndmask_b32_e64 v114, v114, v222, s[16:17]
	v_cmp_lt_i32_e64 s[16:17], v15, v249
	v_cmp_gt_i32_e64 s[18:19], v15, v204
	v_add_u32_e32 v15, 0x63, v14
	v_cmp_lt_i32_e64 s[20:21], v15, v249
	v_cmp_gt_i32_e64 s[22:23], v15, v204
	s_or_b64 s[20:21], s[20:21], s[22:23]
	v_add_u32_e32 v15, 0x48, v14
	v_cndmask_b32_e64 v115, v115, v222, s[20:21]
	v_cmp_lt_i32_e64 s[20:21], v15, v249
	v_cmp_gt_i32_e64 s[22:23], v15, v204
	v_add_u32_e32 v15, 0x68, v14
	v_cmp_lt_i32_e64 s[24:25], v15, v249
	v_cmp_gt_i32_e64 s[26:27], v15, v204
	s_or_b64 s[24:25], s[24:25], s[26:27]
	v_add_u32_e32 v15, 0x49, v14
	v_cndmask_b32_e64 v116, v116, v222, s[24:25]
	v_cmp_lt_i32_e64 s[24:25], v15, v249
	v_cmp_gt_i32_e64 s[26:27], v15, v204
	v_add_u32_e32 v15, 0x69, v14
	v_cmp_lt_i32_e64 s[28:29], v15, v249
	v_cmp_gt_i32_e64 s[30:31], v15, v204
	s_or_b64 s[28:29], s[28:29], s[30:31]
	v_add_u32_e32 v15, 0x4a, v14
	v_cndmask_b32_e64 v117, v117, v222, s[28:29]
	v_cmp_lt_i32_e64 s[28:29], v15, v249
	v_cmp_gt_i32_e64 s[30:31], v15, v204
	v_add_u32_e32 v15, 0x6a, v14
	v_cmp_lt_i32_e64 s[34:35], v15, v249
	v_cmp_gt_i32_e64 s[36:37], v15, v204
	s_or_b64 s[34:35], s[34:35], s[36:37]
	v_add_u32_e32 v15, 0x4b, v14
	v_cndmask_b32_e64 v118, v118, v222, s[34:35]
	v_cmp_lt_i32_e64 s[34:35], v15, v249
	v_cmp_gt_i32_e64 s[36:37], v15, v204
	v_add_u32_e32 v15, 0x6b, v14
	v_cmp_lt_i32_e64 s[38:39], v15, v249
	v_cmp_gt_i32_e64 s[40:41], v15, v204
	s_or_b64 s[38:39], s[38:39], s[40:41]
	v_add_u32_e32 v15, 0x50, v14
	v_cndmask_b32_e64 v119, v119, v222, s[38:39]
	v_cmp_lt_i32_e64 s[38:39], v15, v249
	v_cmp_gt_i32_e64 s[40:41], v15, v204
	v_add_u32_e32 v15, 0x70, v14
	v_cmp_lt_i32_e64 s[42:43], v15, v249
	v_cmp_gt_i32_e64 s[44:45], v15, v204
	s_or_b64 s[42:43], s[42:43], s[44:45]
	v_add_u32_e32 v15, 0x51, v14
	v_cndmask_b32_e64 v120, v120, v222, s[42:43]
	v_cmp_lt_i32_e64 s[42:43], v15, v249
	v_cmp_gt_i32_e64 s[44:45], v15, v204
	v_add_u32_e32 v15, 0x71, v14
	v_cmp_lt_i32_e64 s[46:47], v15, v249
	v_cmp_gt_i32_e64 s[48:49], v15, v204
	s_or_b64 s[46:47], s[46:47], s[48:49]
	v_add_u32_e32 v15, 0x52, v14
	v_cndmask_b32_e64 v121, v121, v222, s[46:47]
	v_cmp_lt_i32_e64 s[46:47], v15, v249
	v_cmp_gt_i32_e64 s[48:49], v15, v204
	v_add_u32_e32 v15, 0x72, v14
	v_cmp_lt_i32_e64 s[50:51], v15, v249
	v_cmp_gt_i32_e64 s[52:53], v15, v204
	s_or_b64 s[50:51], s[50:51], s[52:53]
	v_add_u32_e32 v15, 0x53, v14
	v_cndmask_b32_e64 v122, v122, v222, s[50:51]
	v_cmp_lt_i32_e64 s[50:51], v15, v249
	v_cmp_gt_i32_e64 s[52:53], v15, v204
	v_add_u32_e32 v15, 0x73, v14
	v_cmp_lt_i32_e64 s[54:55], v15, v249
	v_cmp_gt_i32_e64 s[56:57], v15, v204
	s_or_b64 s[54:55], s[54:55], s[56:57]
	v_add_u32_e32 v15, 0x58, v14
	v_cndmask_b32_e64 v123, v123, v222, s[54:55]
	v_cmp_lt_i32_e64 s[54:55], v15, v249
	v_cmp_gt_i32_e64 s[56:57], v15, v204
	v_add_u32_e32 v15, 0x78, v14
	v_cmp_lt_i32_e64 s[58:59], v15, v249
	v_cmp_gt_i32_e64 s[60:61], v15, v204
	s_or_b64 s[58:59], s[58:59], s[60:61]
	v_add_u32_e32 v15, 0x59, v14
	v_cndmask_b32_e64 v124, v124, v222, s[58:59]
	v_cmp_lt_i32_e64 s[58:59], v15, v249
	v_cmp_gt_i32_e64 s[60:61], v15, v204
	v_add_u32_e32 v15, 0x79, v14
	v_cmp_lt_i32_e64 s[62:63], v15, v249
	v_cmp_gt_i32_e64 s[64:65], v15, v204
	s_or_b64 s[62:63], s[62:63], s[64:65]
	v_add_u32_e32 v15, 0x5a, v14
	v_cndmask_b32_e64 v125, v125, v222, s[62:63]
	v_cmp_lt_i32_e64 s[62:63], v15, v249
	v_cmp_gt_i32_e64 s[64:65], v15, v204
	v_add_u32_e32 v15, 0x7a, v14
	v_add_u32_e32 v250, 0x41, v14
	v_cmp_lt_i32_e64 s[66:67], v15, v249
	v_cmp_gt_i32_e64 s[68:69], v15, v204
	v_add_u32_e32 v15, 0x5b, v14
	v_add_u32_e32 v14, 0x7b, v14
	s_or_b64 s[66:67], s[66:67], s[68:69]
	v_cmp_lt_i32_e64 s[72:73], v14, v249
	v_cmp_gt_i32_e64 s[74:75], v14, v204
	v_cndmask_b32_e64 v112, v112, v222, s[8:9]
	v_cmp_lt_i32_e64 s[8:9], v250, v249
	v_cndmask_b32_e64 v126, v126, v222, s[66:67]
	v_cmp_lt_i32_e64 s[66:67], v15, v249
	v_cmp_gt_i32_e64 s[68:69], v15, v204
	s_or_b64 s[74:75], s[72:73], s[74:75]
	s_and_saveexec_b64 s[72:73], s[74:75]
	s_mov_b32 s74, 0xf149f2ca
	v_mov_b32_e32 v127, s74
	s_or_b64 exec, exec, s[72:73]
	s_or_b64 vcc, vcc, s[6:7]
	v_cndmask_b32_e32 v128, v128, v222, vcc
	s_or_b64 vcc, s[10:11], s[8:9]
	v_cndmask_b32_e32 v129, v129, v222, vcc
	s_or_b64 vcc, s[12:13], s[14:15]
	v_cndmask_b32_e32 v130, v130, v222, vcc
	s_or_b64 vcc, s[16:17], s[18:19]
	v_cndmask_b32_e32 v131, v131, v222, vcc
	s_or_b64 vcc, s[20:21], s[22:23]
	v_cndmask_b32_e32 v132, v132, v222, vcc
	s_or_b64 vcc, s[24:25], s[26:27]
	v_cndmask_b32_e32 v133, v133, v222, vcc
	s_or_b64 vcc, s[28:29], s[30:31]
	v_cndmask_b32_e32 v134, v134, v222, vcc
	s_or_b64 vcc, s[34:35], s[36:37]
	v_cndmask_b32_e32 v135, v135, v222, vcc
	s_or_b64 vcc, s[38:39], s[40:41]
	v_cndmask_b32_e32 v136, v136, v222, vcc
	s_or_b64 vcc, s[42:43], s[44:45]
	v_cndmask_b32_e32 v137, v137, v222, vcc
	s_or_b64 vcc, s[46:47], s[48:49]
	v_cndmask_b32_e32 v138, v138, v222, vcc
	s_or_b64 vcc, s[50:51], s[52:53]
	v_cndmask_b32_e32 v139, v139, v222, vcc
	s_or_b64 vcc, s[54:55], s[56:57]
	v_cndmask_b32_e32 v140, v140, v222, vcc
	s_or_b64 vcc, s[58:59], s[60:61]
	v_cndmask_b32_e32 v141, v141, v222, vcc
	s_or_b64 vcc, s[62:63], s[64:65]
	v_cndmask_b32_e32 v142, v142, v222, vcc
	s_or_b64 vcc, s[66:67], s[68:69]
	v_cndmask_b32_e32 v143, v143, v222, vcc
	s_mov_b32 s74, 0xc2fc0000

; DI unsigned pk2(float lo, float hi) { f32x2 v = {lo, hi}; return __builtin_bit_cast(unsigned, __builtin_convertvector(v, bf2_t)); }
; DI float fast_exp2(float x) { return __builtin_amdgcn_exp2f(x); }
; #define MFMA32(a, b, c) __builtin_amdgcn_mfma_f32_32x32x16_bf16((a), (b), (c), 0, 0, 0)
; DI void pv_frag(const VFrag& V, const f32x16& p, f32x16& o0, f32x16& o1) {
; #pragma unroll
;     for (int s = 0; s < 2; ++s) {
;         u32x4 pw; pw.x = pk2(p[8 * s], p[8 * s + 1]); pw.y = pk2(p[8 * s + 2], p[8 * s + 3]); pw.z = pk2(p[8 * s + 4], p[8 * s + 5]); pw.w = pk2(p[8 * s + 6], p[8 * s + 7]);
;         const bf16x8 pf = __builtin_bit_cast(bf16x8, pw);
; #pragma unroll
;         for (int d0 = 0; d0 < 2; ++d0) {
;             const u32x2 lo = V.v[(2 * s + d0) * 2], h2 = V.v[(2 * s + d0) * 2 + 1];
;             u32x4 vw; vw.x = lo.x; vw.y = lo.y; vw.z = h2.x; vw.w = h2.y;
;             const bf16x8 vf = __builtin_bit_cast(bf16x8, vw);
;             if (d0 == 0) o0 = MFMA32(vf, pf, o0); else o1 = MFMA32(vf, pf, o1);
;         }
;     }
; }
; DI float soft_update(Soft& f, f32x16& x0, f32x16& x1, bool hasO) {
;     ...
;     float ls = 0.f;
; #pragma unroll
;     for (int r = 0; r < 16; ++r) { x0[r] = fast_exp2(x0[r]); x1[r] = fast_exp2(x1[r]); ls += x0[r] + x1[r]; }
;     f.l += ls;
.LBB0_1030:
	v_exp_f32_e32 v252, v128
	v_exp_f32_e32 v253, v112
	v_exp_f32_e32 v14, v129
	v_exp_f32_e32 v128, v113
	v_mov_b32_e32 v15, v0
	v_add_f32_e32 v129, v253, v252
	s_or_b64 s[4:5], s[4:5], s[6:7]
	v_pk_add_f32 v[112:113], v[128:129], v[14:15]
	v_exp_f32_e32 v15, v130
	v_pk_add_f32 v[250:251], v[112:113], v[112:113] op_sel_hi:[0,1]
	v_exp_f32_e32 v129, v114
	v_exp_f32_e32 v250, v131
	v_exp_f32_e32 v130, v115
	v_add_f32_e32 v131, v129, v15
	v_pk_add_f32 v[112:113], v[130:131], v[250:251]
	s_nop 0
	v_pk_add_f32 v[114:115], v[112:113], v[112:113] op_sel_hi:[0,1]
	v_exp_f32_e32 v131, v132
	v_exp_f32_e32 v251, v116
	v_exp_f32_e32 v114, v133
	v_exp_f32_e32 v116, v117
	v_add_f32_e32 v117, v251, v131
	v_pk_add_f32 v[112:113], v[116:117], v[114:115]
	s_nop 0
	v_pk_add_f32 v[132:133], v[112:113], v[112:113] op_sel_hi:[0,1]
	v_exp_f32_e32 v115, v134
	v_exp_f32_e32 v117, v118
	v_exp_f32_e32 v132, v135
	v_exp_f32_e32 v118, v119
	v_cvt_pk_bf16_f32 v114, v131, v114
	v_add_f32_e32 v119, v117, v115
	v_exp_f32_e32 v131, v124
	v_pk_add_f32 v[112:113], v[118:119], v[132:133]
	v_exp_f32_e32 v119, v136
	v_pk_add_f32 v[134:135], v[112:113], v[112:113] op_sel_hi:[0,1]
	v_exp_f32_e32 v133, v120
	v_exp_f32_e32 v134, v137
	v_exp_f32_e32 v120, v121
	v_cvt_pk_bf16_f32 v115, v115, v132
	v_add_f32_e32 v121, v133, v119
	v_pk_add_f32 v[112:113], v[120:121], v[134:135]
	s_nop 0
	v_pk_add_f32 v[136:137], v[112:113], v[112:113] op_sel_hi:[0,1]
	v_exp_f32_e32 v121, v138
	v_exp_f32_e32 v135, v122
	v_exp_f32_e32 v136, v139
	v_exp_f32_e32 v122, v123
	v_add_f32_e32 v123, v135, v121
	v_pk_add_f32 v[112:113], v[122:123], v[136:137]
	s_nop 0
	v_pk_add_f32 v[138:139], v[112:113], v[112:113] op_sel_hi:[0,1]
	v_exp_f32_e32 v123, v140
	v_cvt_pk_bf16_f32 v112, v252, v14
	v_exp_f32_e32 v138, v141
	v_exp_f32_e32 v14, v125
	v_cvt_pk_bf16_f32 v113, v15, v250
	v_add_f32_e32 v15, v131, v123
	v_pk_add_f32 v[124:125], v[14:15], v[138:139]
	s_waitcnt lgkmcnt(14)
	v_mfma_f32_32x32x16_bf16 v[96:111], v[184:187], v[112:115], v[96:111]
	v_pk_add_f32 v[124:125], v[124:125], v[124:125] op_sel_hi:[0,1]
	v_exp_f32_e32 v15, v142
	v_exp_f32_e32 v124, v143
	s_waitcnt lgkmcnt(10)
	v_mfma_f32_32x32x16_bf16 v[80:95], v[180:183], v[112:115], v[80:95]
	v_cvt_pk_bf16_f32 v112, v119, v134
	v_cvt_pk_bf16_f32 v113, v121, v136
	v_cvt_pk_bf16_f32 v114, v123, v138
	v_cvt_pk_bf16_f32 v115, v15, v124
	s_nop 1
	v_mfma_f32_32x32x16_bf16 v[96:111], v[176:179], v[112:115], v[96:111]
	s_waitcnt lgkmcnt(8)
	v_mfma_f32_32x32x16_bf16 v[80:95], v[172:175], v[112:115], v[80:95]
	v_cvt_pk_bf16_f32 v112, v253, v128
	v_cvt_pk_bf16_f32 v113, v129, v130
	v_cvt_pk_bf16_f32 v114, v251, v116
	v_cvt_pk_bf16_f32 v115, v117, v118
	s_waitcnt lgkmcnt(6)
	s_nop 0
	v_mfma_f32_32x32x16_bf16 v[96:111], v[168:171], v[112:115], v[96:111]
	s_waitcnt lgkmcnt(4)
	v_mfma_f32_32x32x16_bf16 v[80:95], v[10:13], v[112:115], v[80:95]
	v_exp_f32_e32 v113, v126
	v_exp_f32_e32 v112, v127
	v_cvt_pk_bf16_f32 v10, v133, v120
	v_cvt_pk_bf16_f32 v11, v135, v122
	v_cvt_pk_bf16_f32 v12, v131, v14
	v_cvt_pk_bf16_f32 v13, v113, v112
	v_add_f32_e32 v113, v113, v15
	s_waitcnt lgkmcnt(2)
	v_mfma_f32_32x32x16_bf16 v[96:111], v[6:9], v[10:13], v[96:111]
	v_add_f32_e64 v6, v112, v124
	v_add_f32_e64 v7, v113, v125
	v_add_f32_e32 v6, v6, v7
	v_add_f32_e32 v210, v210, v6
	s_waitcnt lgkmcnt(0)
	v_mfma_f32_32x32x16_bf16 v[80:95], v[2:5], v[10:13], v[80:95]
	s_andn2_b64 vcc, exec, s[76:77]
	s_xor_b32 s1, s1, 1
	s_cbranch_vccnz .LBB0_1015
